# speedup vs baseline: 1.0248x; 1.0004x over previous
; __device__ __forceinline__ float bflo(unsigned u) { return __uint_as_float(u << 16); }
; __device__ __forceinline__ float bfhi(unsigned u) { return __uint_as_float(u & 0xffff0000u); }
; __device__ __forceinline__ ushort_t* wsb(const Params& p, size_t off) { return (ushort_t*)(p.ws + off); }
; __device__ __forceinline__ float ret_log2g(int h) { return log2f(1.f - __builtin_amdgcn_exp2f(-5.f - (float)h)); }
; __device__ __forceinline__ void phase_ret_passB(const Params& p) {
;   ushort_t* ST = wsb(p, OFF_P + 5 * SLOT);
;   const long nwork = (long)64 * 256 * 32;
;   for (long w = (long)blockIdx.x * 256 + threadIdx.x; w < nwork; w += (long)gridDim.x * 256) {
;     const int bh = (int)(w >> 13), rem = (int)(w & 8191);
;     const float gC = __builtin_amdgcn_exp2f(128.f * ret_log2g(bh & 3));
;     float run[8];
; #pragma unroll
;     for (int e = 0; e < 8; ++e) run[e] = 0.f;
;     ushort_t* base = ST + (long)bh * 32 * 65536 + (long)rem * 8;
;     for (int c = 0; c < 32; ++c) {
;       u32x4 tv = (u32x4){0u, 0u, 0u, 0u};
;       if (c < 31) tv = *(const u32x4*)(base + (long)c * 65536);
;       u32x4 ov;
;       ov.x = pack2(run[0], run[1]); ov.y = pack2(run[2], run[3]); ov.z = pack2(run[4], run[5]); ov.w = pack2(run[6], run[7]);
;       *(u32x4*)(base + (long)c * 65536) = ov;
;       run[0] = run[0] * gC + bflo(tv.x); run[1] = run[1] * gC + bfhi(tv.x);
;       run[2] = run[2] * gC + bflo(tv.y); run[3] = run[3] * gC + bfhi(tv.y);
;       run[4] = run[4] * gC + bflo(tv.z); run[5] = run[5] * gC + bfhi(tv.z);
;       run[6] = run[6] * gC + bflo(tv.w); run[7] = run[7] * gC + bfhi(tv.w);
;     }
.LBB0_1659:
	s_mov_b64 s[18:19], 0x20000
	v_add_co_u32_e32 v28, vcc, 0x28000000, v6
	s_nop 1
	v_addc_co_u32_e32 v29, vcc, 0, v7, vcc
	v_mov_b32_e32 v8, 0
	v_mov_b32_e32 v9, 0
	v_mov_b32_e32 v10, 0
	v_mov_b32_e32 v11, 0
	v_mov_b32_e32 v12, 0
	v_mov_b32_e32 v13, 0
	v_mov_b32_e32 v14, 0
	v_mov_b32_e32 v15, 0
	v_mov_b32_e32 v30, v28
	v_mov_b32_e32 v31, v29
	global_load_dwordx4 v[32:35], v[28:29], off
	v_lshl_add_u64 v[28:29], v[28:29], 0, s[18:19]
	global_load_dwordx4 v[36:39], v[28:29], off
	v_lshl_add_u64 v[28:29], v[28:29], 0, s[18:19]
	global_load_dwordx4 v[40:43], v[28:29], off
	v_lshl_add_u64 v[28:29], v[28:29], 0, s[18:19]
	global_load_dwordx4 v[44:47], v[28:29], off
	v_lshl_add_u64 v[28:29], v[28:29], 0, s[18:19]
	global_load_dwordx4 v[48:51], v[28:29], off
	v_lshl_add_u64 v[28:29], v[28:29], 0, s[18:19]
	global_load_dwordx4 v[52:55], v[28:29], off
	v_lshl_add_u64 v[28:29], v[28:29], 0, s[18:19]
	global_load_dwordx4 v[56:59], v[28:29], off
	v_lshl_add_u64 v[28:29], v[28:29], 0, s[18:19]
	global_load_dwordx4 v[60:63], v[28:29], off
	v_lshl_add_u64 v[28:29], v[28:29], 0, s[18:19]
	global_load_dwordx4 v[64:67], v[28:29], off
	v_lshl_add_u64 v[28:29], v[28:29], 0, s[18:19]
	global_load_dwordx4 v[68:71], v[28:29], off
	v_lshl_add_u64 v[28:29], v[28:29], 0, s[18:19]
	global_load_dwordx4 v[72:75], v[28:29], off
	v_lshl_add_u64 v[28:29], v[28:29], 0, s[18:19]
	global_load_dwordx4 v[76:79], v[28:29], off
	v_lshl_add_u64 v[28:29], v[28:29], 0, s[18:19]
	global_load_dwordx4 v[80:83], v[28:29], off
	v_lshl_add_u64 v[28:29], v[28:29], 0, s[18:19]
	global_load_dwordx4 v[84:87], v[28:29], off
	v_lshl_add_u64 v[28:29], v[28:29], 0, s[18:19]
	global_load_dwordx4 v[88:91], v[28:29], off
	v_lshl_add_u64 v[28:29], v[28:29], 0, s[18:19]
	global_load_dwordx4 v[92:95], v[28:29], off
	v_lshl_add_u64 v[28:29], v[28:29], 0, s[18:19]
	s_waitcnt vmcnt(15)
	v_cvt_pk_bf16_f32 v24, v8, v9
	v_cvt_pk_bf16_f32 v25, v10, v11
	v_cvt_pk_bf16_f32 v26, v12, v13
	v_cvt_pk_bf16_f32 v27, v14, v15
	global_store_dwordx4 v[30:31], v[24:27], off
	v_lshl_add_u64 v[30:31], v[30:31], 0, s[18:19]
	v_lshlrev_b32_e32 v16, 16, v32
	v_and_b32_e32 v17, 0xffff0000, v32
	v_lshlrev_b32_e32 v18, 16, v33
	v_and_b32_e32 v19, 0xffff0000, v33
	v_lshlrev_b32_e32 v20, 16, v34
	v_and_b32_e32 v21, 0xffff0000, v34
	v_lshlrev_b32_e32 v22, 16, v35
	v_and_b32_e32 v23, 0xffff0000, v35
	v_pk_fma_f32 v[8:9], v[4:5], v[8:9], v[16:17]
	v_pk_fma_f32 v[10:11], v[4:5], v[10:11], v[18:19]
	v_pk_fma_f32 v[12:13], v[4:5], v[12:13], v[20:21]
	v_pk_fma_f32 v[14:15], v[4:5], v[14:15], v[22:23]
	s_waitcnt vmcnt(15)
	v_cvt_pk_bf16_f32 v24, v8, v9
	v_cvt_pk_bf16_f32 v25, v10, v11
	v_cvt_pk_bf16_f32 v26, v12, v13
	v_cvt_pk_bf16_f32 v27, v14, v15
	global_store_dwordx4 v[30:31], v[24:27], off
	v_lshl_add_u64 v[30:31], v[30:31], 0, s[18:19]
	v_lshlrev_b32_e32 v16, 16, v36
	v_and_b32_e32 v17, 0xffff0000, v36
	v_lshlrev_b32_e32 v18, 16, v37
	v_and_b32_e32 v19, 0xffff0000, v37
	v_lshlrev_b32_e32 v20, 16, v38
	v_and_b32_e32 v21, 0xffff0000, v38
	v_lshlrev_b32_e32 v22, 16, v39
	v_and_b32_e32 v23, 0xffff0000, v39
	v_pk_fma_f32 v[8:9], v[4:5], v[8:9], v[16:17]
	v_pk_fma_f32 v[10:11], v[4:5], v[10:11], v[18:19]
	v_pk_fma_f32 v[12:13], v[4:5], v[12:13], v[20:21]
	v_pk_fma_f32 v[14:15], v[4:5], v[14:15], v[22:23]
	s_waitcnt vmcnt(15)
	v_cvt_pk_bf16_f32 v24, v8, v9
	v_cvt_pk_bf16_f32 v25, v10, v11
	v_cvt_pk_bf16_f32 v26, v12, v13
	v_cvt_pk_bf16_f32 v27, v14, v15
	global_store_dwordx4 v[30:31], v[24:27], off
	v_lshl_add_u64 v[30:31], v[30:31], 0, s[18:19]
	v_lshlrev_b32_e32 v16, 16, v40
	v_and_b32_e32 v17, 0xffff0000, v40
	v_lshlrev_b32_e32 v18, 16, v41
	v_and_b32_e32 v19, 0xffff0000, v41
	v_lshlrev_b32_e32 v20, 16, v42
	v_and_b32_e32 v21, 0xffff0000, v42
	v_lshlrev_b32_e32 v22, 16, v43
	v_and_b32_e32 v23, 0xffff0000, v43
	v_pk_fma_f32 v[8:9], v[4:5], v[8:9], v[16:17]
	v_pk_fma_f32 v[10:11], v[4:5], v[10:11], v[18:19]
	v_pk_fma_f32 v[12:13], v[4:5], v[12:13], v[20:21]
	v_pk_fma_f32 v[14:15], v[4:5], v[14:15], v[22:23]
	s_waitcnt vmcnt(15)
	v_cvt_pk_bf16_f32 v24, v8, v9
	v_cvt_pk_bf16_f32 v25, v10, v11
	v_cvt_pk_bf16_f32 v26, v12, v13
	v_cvt_pk_bf16_f32 v27, v14, v15
	global_store_dwordx4 v[30:31], v[24:27], off
	v_lshl_add_u64 v[30:31], v[30:31], 0, s[18:19]
	v_lshlrev_b32_e32 v16, 16, v44
	v_and_b32_e32 v17, 0xffff0000, v44
	v_lshlrev_b32_e32 v18, 16, v45
	v_and_b32_e32 v19, 0xffff0000, v45
	v_lshlrev_b32_e32 v20, 16, v46
	v_and_b32_e32 v21, 0xffff0000, v46
	v_lshlrev_b32_e32 v22, 16, v47
	v_and_b32_e32 v23, 0xffff0000, v47
	v_pk_fma_f32 v[8:9], v[4:5], v[8:9], v[16:17]
	v_pk_fma_f32 v[10:11], v[4:5], v[10:11], v[18:19]
	v_pk_fma_f32 v[12:13], v[4:5], v[12:13], v[20:21]
	v_pk_fma_f32 v[14:15], v[4:5], v[14:15], v[22:23]
	s_waitcnt vmcnt(15)
	v_cvt_pk_bf16_f32 v24, v8, v9
	v_cvt_pk_bf16_f32 v25, v10, v11
	v_cvt_pk_bf16_f32 v26, v12, v13
	v_cvt_pk_bf16_f32 v27, v14, v15
	global_store_dwordx4 v[30:31], v[24:27], off
	v_lshl_add_u64 v[30:31], v[30:31], 0, s[18:19]
	v_lshlrev_b32_e32 v16, 16, v48
	v_and_b32_e32 v17, 0xffff0000, v48
	v_lshlrev_b32_e32 v18, 16, v49
	v_and_b32_e32 v19, 0xffff0000, v49
	v_lshlrev_b32_e32 v20, 16, v50
	v_and_b32_e32 v21, 0xffff0000, v50
	v_lshlrev_b32_e32 v22, 16, v51
	v_and_b32_e32 v23, 0xffff0000, v51
	v_pk_fma_f32 v[8:9], v[4:5], v[8:9], v[16:17]
	v_pk_fma_f32 v[10:11], v[4:5], v[10:11], v[18:19]
	v_pk_fma_f32 v[12:13], v[4:5], v[12:13], v[20:21]
	v_pk_fma_f32 v[14:15], v[4:5], v[14:15], v[22:23]
	s_waitcnt vmcnt(15)
; __device__ __forceinline__ float bflo(unsigned u) { return __uint_as_float(u << 16); }
; __device__ __forceinline__ float bfhi(unsigned u) { return __uint_as_float(u & 0xffff0000u); }
; __device__ __forceinline__ void phase_ret_passB(const Params& p) {
;     ...
;     for (int c = 0; c < 32; ++c) {
;       u32x4 tv = (u32x4){0u, 0u, 0u, 0u};
;       if (c < 31) tv = *(const u32x4*)(base + (long)c * 65536);
;       u32x4 ov;
;       ov.x = pack2(run[0], run[1]); ov.y = pack2(run[2], run[3]); ov.z = pack2(run[4], run[5]); ov.w = pack2(run[6], run[7]);
;       *(u32x4*)(base + (long)c * 65536) = ov;
;       run[0] = run[0] * gC + bflo(tv.x); run[1] = run[1] * gC + bfhi(tv.x);
;       run[2] = run[2] * gC + bflo(tv.y); run[3] = run[3] * gC + bfhi(tv.y);
;       run[4] = run[4] * gC + bflo(tv.z); run[5] = run[5] * gC + bfhi(tv.z);
;       run[6] = run[6] * gC + bflo(tv.w); run[7] = run[7] * gC + bfhi(tv.w);
;     }
	v_cvt_pk_bf16_f32 v24, v8, v9
	v_cvt_pk_bf16_f32 v25, v10, v11
	v_cvt_pk_bf16_f32 v26, v12, v13
	v_cvt_pk_bf16_f32 v27, v14, v15
	global_store_dwordx4 v[30:31], v[24:27], off
	v_lshl_add_u64 v[30:31], v[30:31], 0, s[18:19]
	v_lshlrev_b32_e32 v16, 16, v52
	v_and_b32_e32 v17, 0xffff0000, v52
	v_lshlrev_b32_e32 v18, 16, v53
	v_and_b32_e32 v19, 0xffff0000, v53
	v_lshlrev_b32_e32 v20, 16, v54
	v_and_b32_e32 v21, 0xffff0000, v54
	v_lshlrev_b32_e32 v22, 16, v55
	v_and_b32_e32 v23, 0xffff0000, v55
	v_pk_fma_f32 v[8:9], v[4:5], v[8:9], v[16:17]
	v_pk_fma_f32 v[10:11], v[4:5], v[10:11], v[18:19]
	v_pk_fma_f32 v[12:13], v[4:5], v[12:13], v[20:21]
	v_pk_fma_f32 v[14:15], v[4:5], v[14:15], v[22:23]
	s_waitcnt vmcnt(15)
	v_cvt_pk_bf16_f32 v24, v8, v9
	v_cvt_pk_bf16_f32 v25, v10, v11
	v_cvt_pk_bf16_f32 v26, v12, v13
	v_cvt_pk_bf16_f32 v27, v14, v15
	global_store_dwordx4 v[30:31], v[24:27], off
	v_lshl_add_u64 v[30:31], v[30:31], 0, s[18:19]
	v_lshlrev_b32_e32 v16, 16, v56
	v_and_b32_e32 v17, 0xffff0000, v56
	v_lshlrev_b32_e32 v18, 16, v57
	v_and_b32_e32 v19, 0xffff0000, v57
	v_lshlrev_b32_e32 v20, 16, v58
	v_and_b32_e32 v21, 0xffff0000, v58
	v_lshlrev_b32_e32 v22, 16, v59
	v_and_b32_e32 v23, 0xffff0000, v59
	v_pk_fma_f32 v[8:9], v[4:5], v[8:9], v[16:17]
	v_pk_fma_f32 v[10:11], v[4:5], v[10:11], v[18:19]
	v_pk_fma_f32 v[12:13], v[4:5], v[12:13], v[20:21]
	v_pk_fma_f32 v[14:15], v[4:5], v[14:15], v[22:23]
	s_waitcnt vmcnt(15)
	v_cvt_pk_bf16_f32 v24, v8, v9
	v_cvt_pk_bf16_f32 v25, v10, v11
	v_cvt_pk_bf16_f32 v26, v12, v13
	v_cvt_pk_bf16_f32 v27, v14, v15
	global_store_dwordx4 v[30:31], v[24:27], off
	v_lshl_add_u64 v[30:31], v[30:31], 0, s[18:19]
	v_lshlrev_b32_e32 v16, 16, v60
	v_and_b32_e32 v17, 0xffff0000, v60
	v_lshlrev_b32_e32 v18, 16, v61
	v_and_b32_e32 v19, 0xffff0000, v61
	v_lshlrev_b32_e32 v20, 16, v62
	v_and_b32_e32 v21, 0xffff0000, v62
	v_lshlrev_b32_e32 v22, 16, v63
	v_and_b32_e32 v23, 0xffff0000, v63
	v_pk_fma_f32 v[8:9], v[4:5], v[8:9], v[16:17]
	v_pk_fma_f32 v[10:11], v[4:5], v[10:11], v[18:19]
	v_pk_fma_f32 v[12:13], v[4:5], v[12:13], v[20:21]
	v_pk_fma_f32 v[14:15], v[4:5], v[14:15], v[22:23]
	s_waitcnt vmcnt(15)
	v_cvt_pk_bf16_f32 v24, v8, v9
	v_cvt_pk_bf16_f32 v25, v10, v11
	v_cvt_pk_bf16_f32 v26, v12, v13
	v_cvt_pk_bf16_f32 v27, v14, v15
	global_store_dwordx4 v[30:31], v[24:27], off
	v_lshl_add_u64 v[30:31], v[30:31], 0, s[18:19]
	v_lshlrev_b32_e32 v16, 16, v64
	v_and_b32_e32 v17, 0xffff0000, v64
	v_lshlrev_b32_e32 v18, 16, v65
	v_and_b32_e32 v19, 0xffff0000, v65
	v_lshlrev_b32_e32 v20, 16, v66
	v_and_b32_e32 v21, 0xffff0000, v66
	v_lshlrev_b32_e32 v22, 16, v67
	v_and_b32_e32 v23, 0xffff0000, v67
	v_pk_fma_f32 v[8:9], v[4:5], v[8:9], v[16:17]
	v_pk_fma_f32 v[10:11], v[4:5], v[10:11], v[18:19]
	v_pk_fma_f32 v[12:13], v[4:5], v[12:13], v[20:21]
	v_pk_fma_f32 v[14:15], v[4:5], v[14:15], v[22:23]
	s_waitcnt vmcnt(15)
	v_cvt_pk_bf16_f32 v24, v8, v9
	v_cvt_pk_bf16_f32 v25, v10, v11
	v_cvt_pk_bf16_f32 v26, v12, v13
	v_cvt_pk_bf16_f32 v27, v14, v15
	global_store_dwordx4 v[30:31], v[24:27], off
	v_lshl_add_u64 v[30:31], v[30:31], 0, s[18:19]
	v_lshlrev_b32_e32 v16, 16, v68
	v_and_b32_e32 v17, 0xffff0000, v68
	v_lshlrev_b32_e32 v18, 16, v69
	v_and_b32_e32 v19, 0xffff0000, v69
	v_lshlrev_b32_e32 v20, 16, v70
	v_and_b32_e32 v21, 0xffff0000, v70
	v_lshlrev_b32_e32 v22, 16, v71
	v_and_b32_e32 v23, 0xffff0000, v71
	v_pk_fma_f32 v[8:9], v[4:5], v[8:9], v[16:17]
	v_pk_fma_f32 v[10:11], v[4:5], v[10:11], v[18:19]
	v_pk_fma_f32 v[12:13], v[4:5], v[12:13], v[20:21]
	v_pk_fma_f32 v[14:15], v[4:5], v[14:15], v[22:23]
	s_waitcnt vmcnt(15)
	v_cvt_pk_bf16_f32 v24, v8, v9
	v_cvt_pk_bf16_f32 v25, v10, v11
	v_cvt_pk_bf16_f32 v26, v12, v13
	v_cvt_pk_bf16_f32 v27, v14, v15
	global_store_dwordx4 v[30:31], v[24:27], off
	v_lshl_add_u64 v[30:31], v[30:31], 0, s[18:19]
	v_lshlrev_b32_e32 v16, 16, v72
	v_and_b32_e32 v17, 0xffff0000, v72
	v_lshlrev_b32_e32 v18, 16, v73
	v_and_b32_e32 v19, 0xffff0000, v73
	v_lshlrev_b32_e32 v20, 16, v74
	v_and_b32_e32 v21, 0xffff0000, v74
	v_lshlrev_b32_e32 v22, 16, v75
	v_and_b32_e32 v23, 0xffff0000, v75
	v_pk_fma_f32 v[8:9], v[4:5], v[8:9], v[16:17]
	v_pk_fma_f32 v[10:11], v[4:5], v[10:11], v[18:19]
	v_pk_fma_f32 v[12:13], v[4:5], v[12:13], v[20:21]
	v_pk_fma_f32 v[14:15], v[4:5], v[14:15], v[22:23]
	s_waitcnt vmcnt(15)
	v_cvt_pk_bf16_f32 v24, v8, v9
	v_cvt_pk_bf16_f32 v25, v10, v11
	v_cvt_pk_bf16_f32 v26, v12, v13
	v_cvt_pk_bf16_f32 v27, v14, v15
	global_store_dwordx4 v[30:31], v[24:27], off
	v_lshl_add_u64 v[30:31], v[30:31], 0, s[18:19]
	v_lshlrev_b32_e32 v16, 16, v76
	v_and_b32_e32 v17, 0xffff0000, v76
	v_lshlrev_b32_e32 v18, 16, v77
	v_and_b32_e32 v19, 0xffff0000, v77
	v_lshlrev_b32_e32 v20, 16, v78
	v_and_b32_e32 v21, 0xffff0000, v78
	v_lshlrev_b32_e32 v22, 16, v79
	v_and_b32_e32 v23, 0xffff0000, v79
	v_pk_fma_f32 v[8:9], v[4:5], v[8:9], v[16:17]
	v_pk_fma_f32 v[10:11], v[4:5], v[10:11], v[18:19]
	v_pk_fma_f32 v[12:13], v[4:5], v[12:13], v[20:21]
	v_pk_fma_f32 v[14:15], v[4:5], v[14:15], v[22:23]
	s_waitcnt vmcnt(15)
	v_cvt_pk_bf16_f32 v24, v8, v9
	v_cvt_pk_bf16_f32 v25, v10, v11
	v_cvt_pk_bf16_f32 v26, v12, v13
	v_cvt_pk_bf16_f32 v27, v14, v15
	global_store_dwordx4 v[30:31], v[24:27], off
	v_lshl_add_u64 v[30:31], v[30:31], 0, s[18:19]
	v_lshlrev_b32_e32 v16, 16, v80
	v_and_b32_e32 v17, 0xffff0000, v80
	v_lshlrev_b32_e32 v18, 16, v81
	v_and_b32_e32 v19, 0xffff0000, v81
	v_lshlrev_b32_e32 v20, 16, v82
	v_and_b32_e32 v21, 0xffff0000, v82
	v_lshlrev_b32_e32 v22, 16, v83
	v_and_b32_e32 v23, 0xffff0000, v83
	v_pk_fma_f32 v[8:9], v[4:5], v[8:9], v[16:17]
	v_pk_fma_f32 v[10:11], v[4:5], v[10:11], v[18:19]
	v_pk_fma_f32 v[12:13], v[4:5], v[12:13], v[20:21]
	v_pk_fma_f32 v[14:15], v[4:5], v[14:15], v[22:23]
	s_waitcnt vmcnt(15)
; __device__ __forceinline__ float bflo(unsigned u) { return __uint_as_float(u << 16); }
; __device__ __forceinline__ float bfhi(unsigned u) { return __uint_as_float(u & 0xffff0000u); }
; __device__ __forceinline__ void phase_ret_passB(const Params& p) {
;     ...
;     for (int c = 0; c < 32; ++c) {
;       u32x4 tv = (u32x4){0u, 0u, 0u, 0u};
;       if (c < 31) tv = *(const u32x4*)(base + (long)c * 65536);
;       u32x4 ov;
;       ov.x = pack2(run[0], run[1]); ov.y = pack2(run[2], run[3]); ov.z = pack2(run[4], run[5]); ov.w = pack2(run[6], run[7]);
;       *(u32x4*)(base + (long)c * 65536) = ov;
;       run[0] = run[0] * gC + bflo(tv.x); run[1] = run[1] * gC + bfhi(tv.x);
;       run[2] = run[2] * gC + bflo(tv.y); run[3] = run[3] * gC + bfhi(tv.y);
;       run[4] = run[4] * gC + bflo(tv.z); run[5] = run[5] * gC + bfhi(tv.z);
;       run[6] = run[6] * gC + bflo(tv.w); run[7] = run[7] * gC + bfhi(tv.w);
;     }
	v_cvt_pk_bf16_f32 v24, v8, v9
	v_cvt_pk_bf16_f32 v25, v10, v11
	v_cvt_pk_bf16_f32 v26, v12, v13
	v_cvt_pk_bf16_f32 v27, v14, v15
	global_store_dwordx4 v[30:31], v[24:27], off
	v_lshl_add_u64 v[30:31], v[30:31], 0, s[18:19]
	v_lshlrev_b32_e32 v16, 16, v84
	v_and_b32_e32 v17, 0xffff0000, v84
	v_lshlrev_b32_e32 v18, 16, v85
	v_and_b32_e32 v19, 0xffff0000, v85
	v_lshlrev_b32_e32 v20, 16, v86
	v_and_b32_e32 v21, 0xffff0000, v86
	v_lshlrev_b32_e32 v22, 16, v87
	v_and_b32_e32 v23, 0xffff0000, v87
	v_pk_fma_f32 v[8:9], v[4:5], v[8:9], v[16:17]
	v_pk_fma_f32 v[10:11], v[4:5], v[10:11], v[18:19]
	v_pk_fma_f32 v[12:13], v[4:5], v[12:13], v[20:21]
	v_pk_fma_f32 v[14:15], v[4:5], v[14:15], v[22:23]
	s_waitcnt vmcnt(15)
	v_cvt_pk_bf16_f32 v24, v8, v9
	v_cvt_pk_bf16_f32 v25, v10, v11
	v_cvt_pk_bf16_f32 v26, v12, v13
	v_cvt_pk_bf16_f32 v27, v14, v15
	global_store_dwordx4 v[30:31], v[24:27], off
	v_lshl_add_u64 v[30:31], v[30:31], 0, s[18:19]
	v_lshlrev_b32_e32 v16, 16, v88
	v_and_b32_e32 v17, 0xffff0000, v88
	v_lshlrev_b32_e32 v18, 16, v89
	v_and_b32_e32 v19, 0xffff0000, v89
	v_lshlrev_b32_e32 v20, 16, v90
	v_and_b32_e32 v21, 0xffff0000, v90
	v_lshlrev_b32_e32 v22, 16, v91
	v_and_b32_e32 v23, 0xffff0000, v91
	v_pk_fma_f32 v[8:9], v[4:5], v[8:9], v[16:17]
	v_pk_fma_f32 v[10:11], v[4:5], v[10:11], v[18:19]
	v_pk_fma_f32 v[12:13], v[4:5], v[12:13], v[20:21]
	v_pk_fma_f32 v[14:15], v[4:5], v[14:15], v[22:23]
	s_waitcnt vmcnt(15)
	v_cvt_pk_bf16_f32 v24, v8, v9
	v_cvt_pk_bf16_f32 v25, v10, v11
	v_cvt_pk_bf16_f32 v26, v12, v13
	v_cvt_pk_bf16_f32 v27, v14, v15
	global_store_dwordx4 v[30:31], v[24:27], off
	v_lshl_add_u64 v[30:31], v[30:31], 0, s[18:19]
	v_lshlrev_b32_e32 v16, 16, v92
	v_and_b32_e32 v17, 0xffff0000, v92
	v_lshlrev_b32_e32 v18, 16, v93
	v_and_b32_e32 v19, 0xffff0000, v93
	v_lshlrev_b32_e32 v20, 16, v94
	v_and_b32_e32 v21, 0xffff0000, v94
	v_lshlrev_b32_e32 v22, 16, v95
	v_and_b32_e32 v23, 0xffff0000, v95
	v_pk_fma_f32 v[8:9], v[4:5], v[8:9], v[16:17]
	v_pk_fma_f32 v[10:11], v[4:5], v[10:11], v[18:19]
	v_pk_fma_f32 v[12:13], v[4:5], v[12:13], v[20:21]
	v_pk_fma_f32 v[14:15], v[4:5], v[14:15], v[22:23]
	global_load_dwordx4 v[32:35], v[28:29], off
	v_lshl_add_u64 v[28:29], v[28:29], 0, s[18:19]
	global_load_dwordx4 v[36:39], v[28:29], off
	v_lshl_add_u64 v[28:29], v[28:29], 0, s[18:19]
	global_load_dwordx4 v[40:43], v[28:29], off
	v_lshl_add_u64 v[28:29], v[28:29], 0, s[18:19]
	global_load_dwordx4 v[44:47], v[28:29], off
	v_lshl_add_u64 v[28:29], v[28:29], 0, s[18:19]
	global_load_dwordx4 v[48:51], v[28:29], off
	v_lshl_add_u64 v[28:29], v[28:29], 0, s[18:19]
	global_load_dwordx4 v[52:55], v[28:29], off
	v_lshl_add_u64 v[28:29], v[28:29], 0, s[18:19]
	global_load_dwordx4 v[56:59], v[28:29], off
	v_lshl_add_u64 v[28:29], v[28:29], 0, s[18:19]
	global_load_dwordx4 v[60:63], v[28:29], off
	v_lshl_add_u64 v[28:29], v[28:29], 0, s[18:19]
	global_load_dwordx4 v[64:67], v[28:29], off
	v_lshl_add_u64 v[28:29], v[28:29], 0, s[18:19]
	global_load_dwordx4 v[68:71], v[28:29], off
	v_lshl_add_u64 v[28:29], v[28:29], 0, s[18:19]
	global_load_dwordx4 v[72:75], v[28:29], off
	v_lshl_add_u64 v[28:29], v[28:29], 0, s[18:19]
	global_load_dwordx4 v[76:79], v[28:29], off
	v_lshl_add_u64 v[28:29], v[28:29], 0, s[18:19]
	global_load_dwordx4 v[80:83], v[28:29], off
	v_lshl_add_u64 v[28:29], v[28:29], 0, s[18:19]
	global_load_dwordx4 v[84:87], v[28:29], off
	v_lshl_add_u64 v[28:29], v[28:29], 0, s[18:19]
	global_load_dwordx4 v[88:91], v[28:29], off
	v_lshl_add_u64 v[28:29], v[28:29], 0, s[18:19]
	s_waitcnt vmcnt(14)
	v_cvt_pk_bf16_f32 v24, v8, v9
	v_cvt_pk_bf16_f32 v25, v10, v11
	v_cvt_pk_bf16_f32 v26, v12, v13
	v_cvt_pk_bf16_f32 v27, v14, v15
	global_store_dwordx4 v[30:31], v[24:27], off
	v_lshl_add_u64 v[30:31], v[30:31], 0, s[18:19]
	v_lshlrev_b32_e32 v16, 16, v32
	v_and_b32_e32 v17, 0xffff0000, v32
	v_lshlrev_b32_e32 v18, 16, v33
	v_and_b32_e32 v19, 0xffff0000, v33
	v_lshlrev_b32_e32 v20, 16, v34
	v_and_b32_e32 v21, 0xffff0000, v34
	v_lshlrev_b32_e32 v22, 16, v35
	v_and_b32_e32 v23, 0xffff0000, v35
	v_pk_fma_f32 v[8:9], v[4:5], v[8:9], v[16:17]
	v_pk_fma_f32 v[10:11], v[4:5], v[10:11], v[18:19]
	v_pk_fma_f32 v[12:13], v[4:5], v[12:13], v[20:21]
	v_pk_fma_f32 v[14:15], v[4:5], v[14:15], v[22:23]
	s_waitcnt vmcnt(14)
	v_cvt_pk_bf16_f32 v24, v8, v9
	v_cvt_pk_bf16_f32 v25, v10, v11
	v_cvt_pk_bf16_f32 v26, v12, v13
	v_cvt_pk_bf16_f32 v27, v14, v15
	global_store_dwordx4 v[30:31], v[24:27], off
	v_lshl_add_u64 v[30:31], v[30:31], 0, s[18:19]
	v_lshlrev_b32_e32 v16, 16, v36
	v_and_b32_e32 v17, 0xffff0000, v36
	v_lshlrev_b32_e32 v18, 16, v37
	v_and_b32_e32 v19, 0xffff0000, v37
	v_lshlrev_b32_e32 v20, 16, v38
	v_and_b32_e32 v21, 0xffff0000, v38
	v_lshlrev_b32_e32 v22, 16, v39
	v_and_b32_e32 v23, 0xffff0000, v39
	v_pk_fma_f32 v[8:9], v[4:5], v[8:9], v[16:17]
	v_pk_fma_f32 v[10:11], v[4:5], v[10:11], v[18:19]
	v_pk_fma_f32 v[12:13], v[4:5], v[12:13], v[20:21]
	v_pk_fma_f32 v[14:15], v[4:5], v[14:15], v[22:23]
	s_waitcnt vmcnt(14)
	v_cvt_pk_bf16_f32 v24, v8, v9
	v_cvt_pk_bf16_f32 v25, v10, v11
	v_cvt_pk_bf16_f32 v26, v12, v13
	v_cvt_pk_bf16_f32 v27, v14, v15
	global_store_dwordx4 v[30:31], v[24:27], off
	v_lshl_add_u64 v[30:31], v[30:31], 0, s[18:19]
	v_lshlrev_b32_e32 v16, 16, v40
	v_and_b32_e32 v17, 0xffff0000, v40
	v_lshlrev_b32_e32 v18, 16, v41
	v_and_b32_e32 v19, 0xffff0000, v41
	v_lshlrev_b32_e32 v20, 16, v42
	v_and_b32_e32 v21, 0xffff0000, v42
	v_lshlrev_b32_e32 v22, 16, v43
	v_and_b32_e32 v23, 0xffff0000, v43
	v_pk_fma_f32 v[8:9], v[4:5], v[8:9], v[16:17]
	v_pk_fma_f32 v[10:11], v[4:5], v[10:11], v[18:19]
	v_pk_fma_f32 v[12:13], v[4:5], v[12:13], v[20:21]
	v_pk_fma_f32 v[14:15], v[4:5], v[14:15], v[22:23]
	s_waitcnt vmcnt(14)
; __device__ __forceinline__ float bflo(unsigned u) { return __uint_as_float(u << 16); }
; __device__ __forceinline__ float bfhi(unsigned u) { return __uint_as_float(u & 0xffff0000u); }
; __device__ __forceinline__ void phase_ret_passB(const Params& p) {
;     ...
;     for (int c = 0; c < 32; ++c) {
;       u32x4 tv = (u32x4){0u, 0u, 0u, 0u};
;       if (c < 31) tv = *(const u32x4*)(base + (long)c * 65536);
;       u32x4 ov;
;       ov.x = pack2(run[0], run[1]); ov.y = pack2(run[2], run[3]); ov.z = pack2(run[4], run[5]); ov.w = pack2(run[6], run[7]);
;       *(u32x4*)(base + (long)c * 65536) = ov;
;       run[0] = run[0] * gC + bflo(tv.x); run[1] = run[1] * gC + bfhi(tv.x);
;       run[2] = run[2] * gC + bflo(tv.y); run[3] = run[3] * gC + bfhi(tv.y);
;       run[4] = run[4] * gC + bflo(tv.z); run[5] = run[5] * gC + bfhi(tv.z);
;       run[6] = run[6] * gC + bflo(tv.w); run[7] = run[7] * gC + bfhi(tv.w);
;     }
	v_cvt_pk_bf16_f32 v24, v8, v9
	v_cvt_pk_bf16_f32 v25, v10, v11
	v_cvt_pk_bf16_f32 v26, v12, v13
	v_cvt_pk_bf16_f32 v27, v14, v15
	global_store_dwordx4 v[30:31], v[24:27], off
	v_lshl_add_u64 v[30:31], v[30:31], 0, s[18:19]
	v_lshlrev_b32_e32 v16, 16, v44
	v_and_b32_e32 v17, 0xffff0000, v44
	v_lshlrev_b32_e32 v18, 16, v45
	v_and_b32_e32 v19, 0xffff0000, v45
	v_lshlrev_b32_e32 v20, 16, v46
	v_and_b32_e32 v21, 0xffff0000, v46
	v_lshlrev_b32_e32 v22, 16, v47
	v_and_b32_e32 v23, 0xffff0000, v47
	v_pk_fma_f32 v[8:9], v[4:5], v[8:9], v[16:17]
	v_pk_fma_f32 v[10:11], v[4:5], v[10:11], v[18:19]
	v_pk_fma_f32 v[12:13], v[4:5], v[12:13], v[20:21]
	v_pk_fma_f32 v[14:15], v[4:5], v[14:15], v[22:23]
	s_waitcnt vmcnt(14)
	v_cvt_pk_bf16_f32 v24, v8, v9
	v_cvt_pk_bf16_f32 v25, v10, v11
	v_cvt_pk_bf16_f32 v26, v12, v13
	v_cvt_pk_bf16_f32 v27, v14, v15
	global_store_dwordx4 v[30:31], v[24:27], off
	v_lshl_add_u64 v[30:31], v[30:31], 0, s[18:19]
	v_lshlrev_b32_e32 v16, 16, v48
	v_and_b32_e32 v17, 0xffff0000, v48
	v_lshlrev_b32_e32 v18, 16, v49
	v_and_b32_e32 v19, 0xffff0000, v49
	v_lshlrev_b32_e32 v20, 16, v50
	v_and_b32_e32 v21, 0xffff0000, v50
	v_lshlrev_b32_e32 v22, 16, v51
	v_and_b32_e32 v23, 0xffff0000, v51
	v_pk_fma_f32 v[8:9], v[4:5], v[8:9], v[16:17]
	v_pk_fma_f32 v[10:11], v[4:5], v[10:11], v[18:19]
	v_pk_fma_f32 v[12:13], v[4:5], v[12:13], v[20:21]
	v_pk_fma_f32 v[14:15], v[4:5], v[14:15], v[22:23]
	s_waitcnt vmcnt(14)
	v_cvt_pk_bf16_f32 v24, v8, v9
	v_cvt_pk_bf16_f32 v25, v10, v11
	v_cvt_pk_bf16_f32 v26, v12, v13
	v_cvt_pk_bf16_f32 v27, v14, v15
	global_store_dwordx4 v[30:31], v[24:27], off
	v_lshl_add_u64 v[30:31], v[30:31], 0, s[18:19]
	v_lshlrev_b32_e32 v16, 16, v52
	v_and_b32_e32 v17, 0xffff0000, v52
	v_lshlrev_b32_e32 v18, 16, v53
	v_and_b32_e32 v19, 0xffff0000, v53
	v_lshlrev_b32_e32 v20, 16, v54
	v_and_b32_e32 v21, 0xffff0000, v54
	v_lshlrev_b32_e32 v22, 16, v55
	v_and_b32_e32 v23, 0xffff0000, v55
	v_pk_fma_f32 v[8:9], v[4:5], v[8:9], v[16:17]
	v_pk_fma_f32 v[10:11], v[4:5], v[10:11], v[18:19]
	v_pk_fma_f32 v[12:13], v[4:5], v[12:13], v[20:21]
	v_pk_fma_f32 v[14:15], v[4:5], v[14:15], v[22:23]
	s_waitcnt vmcnt(14)
	v_cvt_pk_bf16_f32 v24, v8, v9
	v_cvt_pk_bf16_f32 v25, v10, v11
	v_cvt_pk_bf16_f32 v26, v12, v13
	v_cvt_pk_bf16_f32 v27, v14, v15
	global_store_dwordx4 v[30:31], v[24:27], off
	v_lshl_add_u64 v[30:31], v[30:31], 0, s[18:19]
	v_lshlrev_b32_e32 v16, 16, v56
	v_and_b32_e32 v17, 0xffff0000, v56
	v_lshlrev_b32_e32 v18, 16, v57
	v_and_b32_e32 v19, 0xffff0000, v57
	v_lshlrev_b32_e32 v20, 16, v58
	v_and_b32_e32 v21, 0xffff0000, v58
	v_lshlrev_b32_e32 v22, 16, v59
	v_and_b32_e32 v23, 0xffff0000, v59
	v_pk_fma_f32 v[8:9], v[4:5], v[8:9], v[16:17]
	v_pk_fma_f32 v[10:11], v[4:5], v[10:11], v[18:19]
	v_pk_fma_f32 v[12:13], v[4:5], v[12:13], v[20:21]
	v_pk_fma_f32 v[14:15], v[4:5], v[14:15], v[22:23]
	s_waitcnt vmcnt(14)
	v_cvt_pk_bf16_f32 v24, v8, v9
	v_cvt_pk_bf16_f32 v25, v10, v11
	v_cvt_pk_bf16_f32 v26, v12, v13
	v_cvt_pk_bf16_f32 v27, v14, v15
	global_store_dwordx4 v[30:31], v[24:27], off
	v_lshl_add_u64 v[30:31], v[30:31], 0, s[18:19]
	v_lshlrev_b32_e32 v16, 16, v60
	v_and_b32_e32 v17, 0xffff0000, v60
	v_lshlrev_b32_e32 v18, 16, v61
	v_and_b32_e32 v19, 0xffff0000, v61
	v_lshlrev_b32_e32 v20, 16, v62
	v_and_b32_e32 v21, 0xffff0000, v62
	v_lshlrev_b32_e32 v22, 16, v63
	v_and_b32_e32 v23, 0xffff0000, v63
	v_pk_fma_f32 v[8:9], v[4:5], v[8:9], v[16:17]
	v_pk_fma_f32 v[10:11], v[4:5], v[10:11], v[18:19]
	v_pk_fma_f32 v[12:13], v[4:5], v[12:13], v[20:21]
	v_pk_fma_f32 v[14:15], v[4:5], v[14:15], v[22:23]
	s_waitcnt vmcnt(14)
	v_cvt_pk_bf16_f32 v24, v8, v9
	v_cvt_pk_bf16_f32 v25, v10, v11
	v_cvt_pk_bf16_f32 v26, v12, v13
	v_cvt_pk_bf16_f32 v27, v14, v15
	global_store_dwordx4 v[30:31], v[24:27], off
	v_lshl_add_u64 v[30:31], v[30:31], 0, s[18:19]
	v_lshlrev_b32_e32 v16, 16, v64
	v_and_b32_e32 v17, 0xffff0000, v64
	v_lshlrev_b32_e32 v18, 16, v65
	v_and_b32_e32 v19, 0xffff0000, v65
	v_lshlrev_b32_e32 v20, 16, v66
	v_and_b32_e32 v21, 0xffff0000, v66
	v_lshlrev_b32_e32 v22, 16, v67
	v_and_b32_e32 v23, 0xffff0000, v67
	v_pk_fma_f32 v[8:9], v[4:5], v[8:9], v[16:17]
	v_pk_fma_f32 v[10:11], v[4:5], v[10:11], v[18:19]
	v_pk_fma_f32 v[12:13], v[4:5], v[12:13], v[20:21]
	v_pk_fma_f32 v[14:15], v[4:5], v[14:15], v[22:23]
	s_waitcnt vmcnt(14)
; __device__ __forceinline__ float bflo(unsigned u) { return __uint_as_float(u << 16); }
; __device__ __forceinline__ float bfhi(unsigned u) { return __uint_as_float(u & 0xffff0000u); }
; __device__ __forceinline__ void phase_ret_passB(const Params& p) {
;     ...
;     for (int c = 0; c < 32; ++c) {
;       u32x4 tv = (u32x4){0u, 0u, 0u, 0u};
;       if (c < 31) tv = *(const u32x4*)(base + (long)c * 65536);
;       u32x4 ov;
;       ov.x = pack2(run[0], run[1]); ov.y = pack2(run[2], run[3]); ov.z = pack2(run[4], run[5]); ov.w = pack2(run[6], run[7]);
;       *(u32x4*)(base + (long)c * 65536) = ov;
;       run[0] = run[0] * gC + bflo(tv.x); run[1] = run[1] * gC + bfhi(tv.x);
;       run[2] = run[2] * gC + bflo(tv.y); run[3] = run[3] * gC + bfhi(tv.y);
;       run[4] = run[4] * gC + bflo(tv.z); run[5] = run[5] * gC + bfhi(tv.z);
;       run[6] = run[6] * gC + bflo(tv.w); run[7] = run[7] * gC + bfhi(tv.w);
;     }
	v_cvt_pk_bf16_f32 v24, v8, v9
	v_cvt_pk_bf16_f32 v25, v10, v11
	v_cvt_pk_bf16_f32 v26, v12, v13
	v_cvt_pk_bf16_f32 v27, v14, v15
	global_store_dwordx4 v[30:31], v[24:27], off
	v_lshl_add_u64 v[30:31], v[30:31], 0, s[18:19]
	v_lshlrev_b32_e32 v16, 16, v68
	v_and_b32_e32 v17, 0xffff0000, v68
	v_lshlrev_b32_e32 v18, 16, v69
	v_and_b32_e32 v19, 0xffff0000, v69
	v_lshlrev_b32_e32 v20, 16, v70
	v_and_b32_e32 v21, 0xffff0000, v70
	v_lshlrev_b32_e32 v22, 16, v71
	v_and_b32_e32 v23, 0xffff0000, v71
	v_pk_fma_f32 v[8:9], v[4:5], v[8:9], v[16:17]
	v_pk_fma_f32 v[10:11], v[4:5], v[10:11], v[18:19]
	v_pk_fma_f32 v[12:13], v[4:5], v[12:13], v[20:21]
	v_pk_fma_f32 v[14:15], v[4:5], v[14:15], v[22:23]
	s_waitcnt vmcnt(14)
	v_cvt_pk_bf16_f32 v24, v8, v9
	v_cvt_pk_bf16_f32 v25, v10, v11
	v_cvt_pk_bf16_f32 v26, v12, v13
	v_cvt_pk_bf16_f32 v27, v14, v15
	global_store_dwordx4 v[30:31], v[24:27], off
	v_lshl_add_u64 v[30:31], v[30:31], 0, s[18:19]
	v_lshlrev_b32_e32 v16, 16, v72
	v_and_b32_e32 v17, 0xffff0000, v72
	v_lshlrev_b32_e32 v18, 16, v73
	v_and_b32_e32 v19, 0xffff0000, v73
	v_lshlrev_b32_e32 v20, 16, v74
	v_and_b32_e32 v21, 0xffff0000, v74
	v_lshlrev_b32_e32 v22, 16, v75
	v_and_b32_e32 v23, 0xffff0000, v75
	v_pk_fma_f32 v[8:9], v[4:5], v[8:9], v[16:17]
	v_pk_fma_f32 v[10:11], v[4:5], v[10:11], v[18:19]
	v_pk_fma_f32 v[12:13], v[4:5], v[12:13], v[20:21]
	v_pk_fma_f32 v[14:15], v[4:5], v[14:15], v[22:23]
	s_waitcnt vmcnt(14)
	v_cvt_pk_bf16_f32 v24, v8, v9
	v_cvt_pk_bf16_f32 v25, v10, v11
	v_cvt_pk_bf16_f32 v26, v12, v13
	v_cvt_pk_bf16_f32 v27, v14, v15
	global_store_dwordx4 v[30:31], v[24:27], off
	v_lshl_add_u64 v[30:31], v[30:31], 0, s[18:19]
	v_lshlrev_b32_e32 v16, 16, v76
	v_and_b32_e32 v17, 0xffff0000, v76
	v_lshlrev_b32_e32 v18, 16, v77
	v_and_b32_e32 v19, 0xffff0000, v77
	v_lshlrev_b32_e32 v20, 16, v78
	v_and_b32_e32 v21, 0xffff0000, v78
	v_lshlrev_b32_e32 v22, 16, v79
	v_and_b32_e32 v23, 0xffff0000, v79
	v_pk_fma_f32 v[8:9], v[4:5], v[8:9], v[16:17]
	v_pk_fma_f32 v[10:11], v[4:5], v[10:11], v[18:19]
	v_pk_fma_f32 v[12:13], v[4:5], v[12:13], v[20:21]
	v_pk_fma_f32 v[14:15], v[4:5], v[14:15], v[22:23]
	s_waitcnt vmcnt(14)
	v_cvt_pk_bf16_f32 v24, v8, v9
	v_cvt_pk_bf16_f32 v25, v10, v11
	v_cvt_pk_bf16_f32 v26, v12, v13
	v_cvt_pk_bf16_f32 v27, v14, v15
	global_store_dwordx4 v[30:31], v[24:27], off
	v_lshl_add_u64 v[30:31], v[30:31], 0, s[18:19]
	v_lshlrev_b32_e32 v16, 16, v80
	v_and_b32_e32 v17, 0xffff0000, v80
	v_lshlrev_b32_e32 v18, 16, v81
	v_and_b32_e32 v19, 0xffff0000, v81
	v_lshlrev_b32_e32 v20, 16, v82
	v_and_b32_e32 v21, 0xffff0000, v82
	v_lshlrev_b32_e32 v22, 16, v83
	v_and_b32_e32 v23, 0xffff0000, v83
	v_pk_fma_f32 v[8:9], v[4:5], v[8:9], v[16:17]
	v_pk_fma_f32 v[10:11], v[4:5], v[10:11], v[18:19]
	v_pk_fma_f32 v[12:13], v[4:5], v[12:13], v[20:21]
	v_pk_fma_f32 v[14:15], v[4:5], v[14:15], v[22:23]
	s_waitcnt vmcnt(14)
	v_cvt_pk_bf16_f32 v24, v8, v9
	v_cvt_pk_bf16_f32 v25, v10, v11
	v_cvt_pk_bf16_f32 v26, v12, v13
	v_cvt_pk_bf16_f32 v27, v14, v15
	global_store_dwordx4 v[30:31], v[24:27], off
	v_lshl_add_u64 v[30:31], v[30:31], 0, s[18:19]
	v_lshlrev_b32_e32 v16, 16, v84
	v_and_b32_e32 v17, 0xffff0000, v84
	v_lshlrev_b32_e32 v18, 16, v85
	v_and_b32_e32 v19, 0xffff0000, v85
	v_lshlrev_b32_e32 v20, 16, v86
	v_and_b32_e32 v21, 0xffff0000, v86
	v_lshlrev_b32_e32 v22, 16, v87
	v_and_b32_e32 v23, 0xffff0000, v87
	v_pk_fma_f32 v[8:9], v[4:5], v[8:9], v[16:17]
	v_pk_fma_f32 v[10:11], v[4:5], v[10:11], v[18:19]
	v_pk_fma_f32 v[12:13], v[4:5], v[12:13], v[20:21]
	v_pk_fma_f32 v[14:15], v[4:5], v[14:15], v[22:23]
	s_waitcnt vmcnt(14)
	v_cvt_pk_bf16_f32 v24, v8, v9
	v_cvt_pk_bf16_f32 v25, v10, v11
	v_cvt_pk_bf16_f32 v26, v12, v13
	v_cvt_pk_bf16_f32 v27, v14, v15
	global_store_dwordx4 v[30:31], v[24:27], off
	v_lshl_add_u64 v[30:31], v[30:31], 0, s[18:19]
	v_lshlrev_b32_e32 v16, 16, v88
	v_and_b32_e32 v17, 0xffff0000, v88
	v_lshlrev_b32_e32 v18, 16, v89
	v_and_b32_e32 v19, 0xffff0000, v89
	v_lshlrev_b32_e32 v20, 16, v90
	v_and_b32_e32 v21, 0xffff0000, v90
	v_lshlrev_b32_e32 v22, 16, v91
	v_and_b32_e32 v23, 0xffff0000, v91
	v_pk_fma_f32 v[8:9], v[4:5], v[8:9], v[16:17]
	v_pk_fma_f32 v[10:11], v[4:5], v[10:11], v[18:19]
	v_pk_fma_f32 v[12:13], v[4:5], v[12:13], v[20:21]
	v_pk_fma_f32 v[14:15], v[4:5], v[14:15], v[22:23]
	s_branch .LBB0_1656
